# v31 + attention unit-epilogue broadcast pk_mul split to scalar muls (16) + sample chunk loop row loads keep zero hi index half (6 v_mov fewer per chunk)
# baseline (speedup 1.0000x reference)
.LBB0_1326:
	v_subrev_u32_e32 v32, 28, v182
	v_min_i32_e32 v32, s53, v32
	v_mad_u32_u24 v32, v32, v177, v178
	v_add_u32_e32 v40, -8, v32
	v_cmp_lt_i32_e32 vcc, v32, v180
	v_add_u32_e32 v211, v127, v129
	ds_read_b128 v[216:219], v211 offset:64
	v_cndmask_b32_e32 v32, v40, v32, vcc
	v_mad_u32_u24 v32, v32, v141, v130
	v_mov_b32_e32 v33, 0
	v_cndmask_b32_e32 v35, v145, v149, vcc
	v_cndmask_b32_e32 v34, v144, v148, vcc
	v_lshl_add_u64 v[34:35], v[32:33], 2, v[34:35]
	global_load_dwordx4 v[112:115], v[34:35], off
	v_cndmask_b32_e32 v35, v147, v151, vcc
	v_cndmask_b32_e32 v34, v146, v150, vcc
	v_lshl_add_u64 v[34:35], v[32:33], 2, v[34:35]
	global_load_dwordx4 v[116:119], v[34:35], off
	v_subrev_u32_e32 v32, 24, v182
	v_min_i32_e32 v32, s53, v32
	v_mad_u32_u24 v32, v32, v177, v178
	v_add_u32_e32 v40, -8, v32
	v_cmp_lt_i32_e32 vcc, v32, v180
	v_min_i32_e32 v120, s53, v182
	v_mul_u32_u24_e32 v120, v120, v177
	v_cndmask_b32_e32 v32, v40, v32, vcc
	v_mad_u32_u24 v32, v32, v141, v130
	v_cndmask_b32_e32 v35, v145, v149, vcc
	v_cndmask_b32_e32 v34, v144, v148, vcc
	v_lshl_add_u64 v[34:35], v[32:33], 2, v[34:35]
	global_load_dwordx4 v[104:107], v[34:35], off
	v_cndmask_b32_e32 v35, v147, v151, vcc
	v_cndmask_b32_e32 v34, v146, v150, vcc
	v_lshl_add_u64 v[34:35], v[32:33], 2, v[34:35]
	global_load_dwordx4 v[108:111], v[34:35], off
	v_subrev_u32_e32 v32, 20, v182
	v_min_i32_e32 v32, s53, v32
	v_mad_u32_u24 v32, v32, v177, v178
	v_add_u32_e32 v40, -8, v32
	v_cmp_lt_i32_e32 vcc, v32, v180
	v_add_u32_e32 v120, v120, v178
	v_add_u32_e32 v209, -8, v120
	v_cndmask_b32_e32 v32, v40, v32, vcc
	v_mad_u32_u24 v32, v32, v141, v130
	v_cndmask_b32_e32 v35, v145, v149, vcc
	v_cndmask_b32_e32 v34, v144, v148, vcc
	v_lshl_add_u64 v[34:35], v[32:33], 2, v[34:35]
	global_load_dwordx4 v[96:99], v[34:35], off
	v_cndmask_b32_e32 v35, v147, v151, vcc
	v_cndmask_b32_e32 v34, v146, v150, vcc
	v_lshl_add_u64 v[34:35], v[32:33], 2, v[34:35]
	global_load_dwordx4 v[100:103], v[34:35], off
	v_add_u32_e32 v32, -16, v182
	v_min_i32_e32 v32, s53, v32
	v_mad_u32_u24 v32, v32, v177, v178
	v_add_u32_e32 v40, -8, v32
	v_cmp_lt_i32_e32 vcc, v32, v180
	v_add_u32_e32 v184, v184, v186
	v_add_u32_e32 v201, v201, v185
	v_cndmask_b32_e32 v32, v40, v32, vcc
	v_mad_u32_u24 v32, v32, v141, v130
	v_cndmask_b32_e32 v35, v145, v149, vcc
	v_cndmask_b32_e32 v34, v144, v148, vcc
	v_lshl_add_u64 v[34:35], v[32:33], 2, v[34:35]
	global_load_dwordx4 v[88:91], v[34:35], off
	v_cndmask_b32_e32 v35, v147, v151, vcc
	v_cndmask_b32_e32 v34, v146, v150, vcc
	v_lshl_add_u64 v[34:35], v[32:33], 2, v[34:35]
	global_load_dwordx4 v[92:95], v[34:35], off
	v_add_u32_e32 v32, -12, v182
	v_min_i32_e32 v32, s53, v32
	v_mad_u32_u24 v32, v32, v177, v178
	v_add_u32_e32 v40, -8, v32
	v_cmp_lt_i32_e32 vcc, v32, v180
	ds_read_b128 v[212:215], v211 offset:32
	v_add_u32_e32 v188, v188, v186
	v_cndmask_b32_e32 v32, v40, v32, vcc
	v_mad_u32_u24 v32, v32, v141, v130
	v_cndmask_b32_e32 v35, v145, v149, vcc
	v_cndmask_b32_e32 v34, v144, v148, vcc
	v_lshl_add_u64 v[34:35], v[32:33], 2, v[34:35]
	global_load_dwordx4 v[80:83], v[34:35], off
	v_cndmask_b32_e32 v35, v147, v151, vcc
	v_cndmask_b32_e32 v34, v146, v150, vcc
	v_lshl_add_u64 v[34:35], v[32:33], 2, v[34:35]
	global_load_dwordx4 v[84:87], v[34:35], off
	v_add_u32_e32 v32, -8, v182
	v_min_i32_e32 v32, s53, v32
	v_mad_u32_u24 v32, v32, v177, v178
	v_add_u32_e32 v40, -8, v32
	v_cmp_lt_i32_e32 vcc, v32, v180
	v_add_u32_e32 v190, v190, v186
	v_add_u32_e32 v192, v192, v186
	v_cndmask_b32_e32 v32, v40, v32, vcc
	v_mad_u32_u24 v32, v32, v141, v130
	v_cndmask_b32_e32 v35, v145, v149, vcc
	v_cndmask_b32_e32 v34, v144, v148, vcc
	v_lshl_add_u64 v[34:35], v[32:33], 2, v[34:35]
	global_load_dwordx4 v[64:67], v[34:35], off
	v_cndmask_b32_e32 v35, v147, v151, vcc
	v_cndmask_b32_e32 v34, v146, v150, vcc
	v_lshl_add_u64 v[34:35], v[32:33], 2, v[34:35]
	global_load_dwordx4 v[68:71], v[34:35], off
	v_add_u32_e32 v32, -4, v182
	v_min_i32_e32 v32, s53, v32
	v_mul_u32_u24_e32 v32, v32, v177
	v_add_u32_e32 v32, v32, v178
	v_add_u32_e32 v33, -8, v32
	v_cmp_lt_i32_e32 vcc, v32, v180
	v_add_u32_e32 v182, 32, v182
	v_add_u32_e32 v194, v194, v186
	v_cndmask_b32_e32 v32, v33, v32, vcc
	v_mul_u32_u24_e32 v32, v32, v141
	v_or_b32_e32 v36, v32, v130
	v_mov_b32_e32 v37, 0
	ds_read_b128 v[32:35], v211
	v_cndmask_b32_e32 v39, v145, v149, vcc
	v_cndmask_b32_e32 v38, v144, v148, vcc
	v_lshlrev_b64 v[76:77], 2, v[36:37]
	v_lshl_add_u64 v[36:37], v[38:39], 0, v[76:77]
	global_load_dwordx4 v[72:75], v[36:37], off
	s_waitcnt lgkmcnt(0)
	v_mfma_f32_32x32x16_bf16 v[32:47], v[32:35], v[56:59], 0
	v_cndmask_b32_e32 v79, v147, v151, vcc
	v_cndmask_b32_e32 v78, v146, v150, vcc
	v_cmp_lt_i32_e32 vcc, v120, v180
	v_lshl_add_u64 v[76:77], v[78:79], 0, v[76:77]
	global_load_dwordx4 v[76:79], v[76:77], off
	v_cndmask_b32_e32 v120, v209, v120, vcc
	v_mul_u32_u24_e32 v220, v120, v141
	v_mfma_f32_32x32x16_bf16 v[32:47], v[212:215], v[60:63], v[32:47]
	ds_read_b128 v[212:215], v211 offset:96
	v_add_u32_e32 v196, v196, v186
	v_add_u32_e32 v198, v198, v186
	v_add_u32_e32 v200, v200, v186
	v_mfma_f32_32x32x16_bf16 v[32:47], v[216:219], v[52:55], v[32:47]
	v_add_u32_e32 v120, s33, v181
	v_cmp_le_u32_e64 s[16:17], v120, v135
	v_or_b32_e32 v218, v220, v130
	v_mov_b32_e32 v219, 0
	v_cndmask_b32_e32 v217, v145, v149, vcc
	s_waitcnt lgkmcnt(0)
	v_mfma_f32_32x32x16_bf16 v[32:47], v[212:215], v[48:51], v[32:47]
	v_cndmask_b32_e32 v216, v144, v148, vcc
	v_lshlrev_b64 v[218:219], 2, v[218:219]
	s_sub_i32 s33, s33, 32
	s_nop 8
	v_cndmask_b32_e64 v210, v173, v32, s[16:17]
	v_add_u32_e32 v32, -1, v120
	v_cmp_le_u32_e64 s[16:17], v32, v135
	s_nop 1
	v_cndmask_b32_e64 v212, v173, v33, s[16:17]
	v_add_u32_e32 v33, -2, v120
	v_cmp_le_u32_e64 s[16:17], v33, v135
	v_add_u32_e32 v33, -3, v120
	v_max3_f32 v32, v210, s90, v212
	v_cndmask_b32_e64 v213, v173, v34, s[16:17]
	v_cmp_le_u32_e64 s[16:17], v33, v135
	v_add_u32_e32 v33, -8, v120
	s_nop 0
	v_cndmask_b32_e64 v214, v173, v35, s[16:17]
	v_cmp_le_u32_e64 s[16:17], v33, v135
	v_add_u32_e32 v33, -9, v120
	v_max3_f32 v32, v32, v213, v214
	v_cndmask_b32_e64 v215, v173, v36, s[16:17]
	v_cmp_le_u32_e64 s[16:17], v33, v135
	v_add_u32_e32 v33, -10, v120
	v_cndmask_b32_e32 v36, v146, v150, vcc
	v_cndmask_b32_e64 v220, v173, v37, s[16:17]
	v_cmp_le_u32_e64 s[16:17], v33, v135
	v_add_u32_e32 v33, -11, v120
	v_max3_f32 v32, v32, v215, v220
	v_cndmask_b32_e64 v221, v173, v38, s[16:17]
	v_cmp_le_u32_e64 s[16:17], v33, v135
	v_add_u32_e32 v33, -16, v120
	v_cndmask_b32_e32 v37, v147, v151, vcc
	v_cndmask_b32_e64 v222, v173, v39, s[16:17]
	v_cmp_le_u32_e64 s[16:17], v33, v135
	v_subrev_u32_e32 v33, 17, v120
	v_max3_f32 v32, v32, v221, v222
	v_cndmask_b32_e64 v40, v173, v40, s[16:17]
	v_cmp_le_u32_e64 s[16:17], v33, v135
	v_subrev_u32_e32 v33, 18, v120
	v_lshl_add_u64 v[36:37], v[36:37], 0, v[218:219]
	v_cndmask_b32_e64 v41, v173, v41, s[16:17]
	v_cmp_le_u32_e64 s[16:17], v33, v135
	v_subrev_u32_e32 v33, 19, v120
	v_max3_f32 v32, v32, v40, v41
	v_cndmask_b32_e64 v42, v173, v42, s[16:17]
	v_cmp_le_u32_e64 s[16:17], v33, v135
	v_subrev_u32_e32 v33, 24, v120
	s_nop 0
	v_cndmask_b32_e64 v43, v173, v43, s[16:17]
	v_cmp_le_u32_e64 s[16:17], v33, v135
	v_subrev_u32_e32 v33, 25, v120
	v_max3_f32 v32, v32, v42, v43
	v_cndmask_b32_e64 v44, v173, v44, s[16:17]
	v_cmp_le_u32_e64 s[16:17], v33, v135
	v_subrev_u32_e32 v33, 26, v120
	s_nop 0
	v_cndmask_b32_e64 v45, v173, v45, s[16:17]
	v_cmp_le_u32_e64 s[16:17], v33, v135
	v_subrev_u32_e32 v33, 27, v120
	v_max3_f32 v32, v32, v44, v45
	v_cndmask_b32_e64 v46, v173, v46, s[16:17]
	v_cmp_le_u32_e64 s[16:17], v33, v135
	s_nop 1
	v_cndmask_b32_e64 v47, v173, v47, s[16:17]
	v_max3_f32 v38, v32, v46, v47
	v_mov_b32_e32 v39, v38
	s_nop 1
	v_permlane32_swap_b32_e32 v39, v38
	v_lshl_add_u64 v[32:33], v[216:217], 0, v[218:219]
	global_load_dwordx4 v[32:35], v[32:33], off
	s_add_i32 s16, s18, s33
	s_cmp_lg_u32 s16, 0
	s_waitcnt lgkmcnt(0)
	v_max3_f32 v209, v208, v38, v39
	v_sub_f32_e32 v38, v210, v209
	v_exp_f32_e32 v210, v38
	global_load_dwordx4 v[36:39], v[36:37], off
	v_sub_f32_e32 v212, v212, v209
	v_exp_f32_e32 v212, v212
	v_sub_f32_e32 v213, v213, v209
	v_exp_f32_e32 v213, v213
	v_sub_f32_e32 v214, v214, v209
	v_exp_f32_e32 v214, v214
	v_sub_f32_e32 v215, v215, v209
	v_sub_f32_e32 v120, v208, v209
	v_add_f32_e32 v208, 0, v210
	v_exp_f32_e32 v215, v215
	v_sub_f32_e32 v216, v220, v209
	v_add_f32_e32 v208, v212, v208
	v_exp_f32_e32 v216, v216
	v_sub_f32_e32 v217, v221, v209
	v_add_f32_e32 v208, v213, v208
	v_exp_f32_e32 v217, v217
	v_sub_f32_e32 v218, v222, v209
	v_add_f32_e32 v208, v214, v208
	v_exp_f32_e32 v218, v218
	v_sub_f32_e32 v40, v40, v209
	v_add_f32_e32 v208, v215, v208
	v_exp_f32_e32 v220, v40
	v_sub_f32_e32 v41, v41, v209
	v_add_f32_e32 v40, v216, v208
	v_exp_f32_e32 v208, v41
	v_sub_f32_e32 v41, v42, v209
	v_add_f32_e32 v40, v217, v40
	v_exp_f32_e32 v221, v41
	v_sub_f32_e32 v41, v43, v209
	v_add_f32_e32 v40, v218, v40
	v_exp_f32_e32 v222, v41
	v_sub_f32_e32 v41, v44, v209
	v_add_f32_e32 v40, v220, v40
	v_exp_f32_e32 v223, v41
	v_sub_f32_e32 v41, v45, v209
	v_add_f32_e32 v40, v208, v40
	v_exp_f32_e32 v224, v41
	v_sub_f32_e32 v41, v46, v209
	v_add_f32_e32 v40, v221, v40
	v_exp_f32_e32 v225, v41
	v_sub_f32_e32 v41, v47, v209
	v_add_f32_e32 v40, v222, v40
	v_exp_f32_e32 v226, v41
	v_add_f32_e32 v40, v223, v40
	v_add_f32_e32 v40, v224, v40
	v_add_f32_e32 v40, v225, v40
	v_exp_f32_e32 v120, v120
	v_add_f32_e32 v227, v226, v40
	ds_read_b64_tr_b16 v[40:41], v175 offset:4608
	ds_read_b64_tr_b16 v[42:43], v175 offset:5760
	v_cvt_pk_bf16_f32 v44, v210, v212
	v_cvt_pk_bf16_f32 v45, v213, v214
	v_cvt_pk_bf16_f32 v46, v215, v216
	v_cvt_pk_bf16_f32 v47, v217, v218
	ds_read_b64_tr_b16 v[212:213], v175 offset:6912
	ds_read_b64_tr_b16 v[214:215], v175 offset:8064
	ds_read_b64_tr_b16 v[218:219], v175 offset:5824
	ds_read_b64_tr_b16 v[216:217], v175 offset:4672
	v_mul_f32_e32 v14, v120, v14
	v_mul_f32_e32 v15, v120, v15
	v_mul_f32_e32 v12, v120, v12
	v_mul_f32_e32 v13, v120, v13
	v_mul_f32_e32 v10, v120, v10
	v_mul_f32_e32 v11, v120, v11
	v_mul_f32_e32 v8, v120, v8
	v_mul_f32_e32 v9, v120, v9
	v_mul_f32_e32 v6, v120, v6
	v_mul_f32_e32 v7, v120, v7
	v_mul_f32_e32 v4, v120, v4
	v_mul_f32_e32 v5, v120, v5
	v_mul_f32_e32 v2, v120, v2
	v_mul_f32_e32 v3, v120, v3
	v_mul_f32_e32 v0, v120, v0
	v_mul_f32_e32 v1, v120, v1
	v_mul_f32_e32 v30, v120, v30
	v_mul_f32_e32 v31, v120, v31
	v_mul_f32_e32 v28, v120, v28
	v_mul_f32_e32 v29, v120, v29
	v_mul_f32_e32 v26, v120, v26
	v_mul_f32_e32 v27, v120, v27
	v_mul_f32_e32 v24, v120, v24
	v_mul_f32_e32 v25, v120, v25
	v_mul_f32_e32 v22, v120, v22
	v_mul_f32_e32 v23, v120, v23
	v_mul_f32_e32 v20, v120, v20
	v_mul_f32_e32 v21, v120, v21
	v_mul_f32_e32 v18, v120, v18
	v_mul_f32_e32 v19, v120, v19
	v_mul_f32_e32 v16, v120, v16
	v_mul_f32_e32 v17, v120, v17
	s_waitcnt lgkmcnt(4)
	v_mfma_f32_32x32x16_bf16 v[0:15], v[40:43], v[44:47], v[0:15]
	v_cvt_pk_bf16_f32 v40, v220, v208
	v_cvt_pk_bf16_f32 v41, v221, v222
	v_cvt_pk_bf16_f32 v42, v223, v224
	ds_read_b64_tr_b16 v[222:223], v175 offset:8128
	ds_read_b64_tr_b16 v[220:221], v175 offset:6976
	v_cvt_pk_bf16_f32 v43, v225, v226
	s_waitcnt lgkmcnt(2)
	v_mfma_f32_32x32x16_bf16 v[16:31], v[216:219], v[44:47], v[16:31]
	v_mov_b32_e32 v44, v227
	s_nop 1
	v_permlane32_swap_b32_e32 v44, v227
	s_waitcnt lgkmcnt(0)
	v_add_f32_e32 v210, v227, v44
	v_fmac_f32_e32 v210, v202, v120
	v_mfma_f32_32x32x16_bf16 v[0:15], v[212:215], v[40:43], v[0:15]
	v_mfma_f32_32x32x16_bf16 v[16:31], v[220:223], v[40:43], v[16:31]
	s_cbranch_scc0 .LBB0_1328
	v_mov_b32_e32 v208, v209
	v_mov_b32_e32 v202, v210
	s_branch .LBB0_1284

.LBB0_1377:
	v_mov_b32_e32 v135, v121
	v_mul_f32_e32 v0, v32, v0
	v_mul_f32_e32 v1, v32, v1
	v_mul_f32_e32 v2, v32, v2
	v_mul_f32_e32 v3, v32, v3
	v_lshl_add_u64 v[34:35], v[34:35], 0, v[134:135]
	v_mul_f32_e32 v16, v32, v16
	v_mul_f32_e32 v17, v32, v17
	v_mul_f32_e32 v18, v32, v18
	v_mul_f32_e32 v19, v32, v19
	v_cvt_pk_bf16_f32 v0, v0, v1
	v_cvt_pk_bf16_f32 v1, v2, v3
	global_store_dwordx2 v[34:35], v[0:1], off
	v_cvt_pk_bf16_f32 v0, v16, v17
	v_cvt_pk_bf16_f32 v1, v18, v19
	global_store_dwordx2 v[34:35], v[0:1], off offset:64
	v_mul_f32_e32 v0, v32, v4
	v_mul_f32_e32 v1, v32, v5
	v_mul_f32_e32 v2, v32, v6
	v_mul_f32_e32 v3, v32, v7
	v_mul_f32_e32 v4, v32, v20
	v_mul_f32_e32 v5, v32, v21
	v_mul_f32_e32 v6, v32, v22
	v_mul_f32_e32 v7, v32, v23
	v_cvt_pk_bf16_f32 v0, v0, v1
	v_cvt_pk_bf16_f32 v1, v2, v3
	global_store_dwordx2 v[34:35], v[0:1], off offset:16
	v_cvt_pk_bf16_f32 v0, v4, v5
	v_cvt_pk_bf16_f32 v1, v6, v7
	global_store_dwordx2 v[34:35], v[0:1], off offset:80
	v_mul_f32_e32 v0, v32, v8
	v_mul_f32_e32 v1, v32, v9
	v_mul_f32_e32 v2, v32, v10
	v_mul_f32_e32 v3, v32, v11
	v_mul_f32_e32 v4, v32, v24
	v_mul_f32_e32 v5, v32, v25
	v_mul_f32_e32 v6, v32, v26
	v_mul_f32_e32 v7, v32, v27
	v_cvt_pk_bf16_f32 v0, v0, v1
	v_cvt_pk_bf16_f32 v1, v2, v3
	global_store_dwordx2 v[34:35], v[0:1], off offset:32
	v_cvt_pk_bf16_f32 v0, v4, v5
	v_cvt_pk_bf16_f32 v1, v6, v7
	global_store_dwordx2 v[34:35], v[0:1], off offset:96
	v_mul_f32_e32 v0, v32, v12
	v_mul_f32_e32 v1, v32, v13
	v_mul_f32_e32 v2, v32, v14
	v_mul_f32_e32 v3, v32, v15
	v_mul_f32_e32 v4, v32, v28
	v_mul_f32_e32 v5, v32, v29
	v_mul_f32_e32 v6, v32, v30
	v_mul_f32_e32 v7, v32, v31
	v_cvt_pk_bf16_f32 v0, v0, v1
	v_cvt_pk_bf16_f32 v1, v2, v3
	global_store_dwordx2 v[34:35], v[0:1], off offset:48
	v_cvt_pk_bf16_f32 v0, v4, v5
	v_cvt_pk_bf16_f32 v1, v6, v7
	global_store_dwordx2 v[34:35], v[0:1], off offset:112
	s_and_b64 exec, exec, s[10:11]
	s_cbranch_execz .LBB0_1210
	v_mov_b32_e32 v141, v121
	v_mad_u64_u32 v[0:1], s[10:11], v176, s94, v[140:141]
	v_mad_u64_u32 v[2:3], s[10:11], v0, 48, s[66:67]
	v_ashrrev_i32_e32 v139, 31, v138
	v_mad_u32_u24 v3, v1, 48, v3
	v_lshl_add_u64 v[0:1], v[138:139], 3, v[2:3]
	global_store_dwordx2 v[0:1], v[40:41], off
	s_branch .LBB0_1210
